# retention: q stored column-permuted in LDS so cross-chunk step reads q frags with ds_read_b128 (k frags as lo/hi halves in score step)
# baseline (speedup 1.0000x reference)
; __device__ __forceinline__ void ret_unit(LAS unsigned char* lds, bf16_t* QKV, float* gn, int b, int h, int vs, bool commit, const float* s00p, const float* ss3, bool skel = false) {
;     ...
;     const int si = w & 3, ti0 = 2 * (w >> 2);
;     u32x4 pq[4], pkv[4], pv[2];
;     const int ls = tid & 63, lc8 = tid >> 6;
.LBB0_1130:
	v_readlane_b32 s52, v254, 6
	s_cmp_lt_i32 s52, 10
	s_cselect_b64 s[6:7], -1, 0
	s_add_u32 s0, s50, 0x180000
	s_addc_u32 s1, s51, 0
	s_and_b64 s[34:35], s[6:7], s[4:5]
	s_xor_b64 s[4:5], s[34:35], -1
	s_cmpk_gt_i32 s2, 0xff
	s_cselect_b64 s[6:7], -1, 0
	s_or_b64 s[4:5], s[4:5], s[6:7]
	v_readlane_b32 s53, v254, 7
	v_readlane_b32 s54, v254, 8
	v_readlane_b32 s55, v254, 9
	s_and_b64 vcc, exec, s[4:5]
	s_cbranch_vccnz .LBB0_1160
	v_and_b32_e32 v128, 63, v176
	s_add_u32 s33, s50, 0x60000
	v_mul_u32_u24_e32 v2, 0x108, v128
	s_addc_u32 s70, s51, 0
	v_bfe_u32 v3, v176, 6, 2
	s_add_i32 s38, 0, 0x10800
	v_lshlrev_b32_e32 v4, 1, v2
	v_lshlrev_b32_e32 v2, 4, v224
	v_and_b32_e32 v130, 15, v176
	v_add3_u32 v129, s38, v4, v2
	v_add3_u32 v131, 0, v4, v2
	v_mul_u32_u24_e32 v4, 0x110, v128
	s_add_i32 s8, 0, 0x18c00
	v_lshlrev_b32_e32 v6, 4, v3
	s_waitcnt lgkmcnt(0)
	v_bfe_u32 v1, v176, 4, 2
	v_add3_u32 v135, s8, v4, v2
	v_or_b32_e32 v4, v6, v130
	s_waitcnt vmcnt(0)
	v_lshlrev_b32_e32 v10, 5, v224
	v_and_b32_e32 v12, 1, v176
	v_mul_u32_u24_e32 v163, 0x210, v4
	v_lshlrev_b32_e32 v4, 2, v1
	v_add_u32_e32 v11, s8, v10
	v_lshlrev_b32_e32 v132, 2, v12
	v_lshrrev_b32_e32 v12, 3, v176
	s_movk_i32 s8, 0x60
	v_lshlrev_b32_e32 v5, 2, v176
	s_add_i32 s71, 0, 0x23800
	v_lshlrev_b32_e32 v164, 3, v1
	v_and_b32_e32 v7, 48, v176
	v_or_b32_e32 v1, v6, v4
	v_and_or_b32 v12, v12, s8, v130
	v_add_u32_e32 v162, s71, v5
	s_movk_i32 s42, 0x210
	v_add_u32_e32 v8, s38, v7
	s_add_i32 s9, 0, 0x21400
	v_lshlrev_b32_e32 v6, 5, v3
	v_and_b32_e32 v5, 12, v5
	v_or_b32_e32 v14, 16, v12
	v_or_b32_e32 v15, 2, v1
	v_or_b32_e32 v16, 3, v1
	v_add3_u32 v6, s9, v6, v164
	v_lshlrev_b32_e32 v165, 1, v5
	v_add_u32_e32 v5, s9, v7
	v_mul_u32_u24_e32 v13, 0x210, v12
	v_mad_u32_u24 v167, v12, s42, v8
	v_cmp_lt_u32_e64 s[8:9], v12, v1
	v_cmp_gt_u32_e64 s[10:11], v12, v1
	v_cmp_lt_u32_e64 s[12:13], v12, v15
	v_cmp_lt_u32_e64 s[14:15], v12, v16
	v_or_b32_e32 v169, v12, v3
	v_mul_u32_u24_e32 v3, 0x90, v12
	v_cmp_lt_u32_e64 s[16:17], v14, v1
	v_cmp_gt_u32_e64 s[18:19], v14, v1
	v_cmp_lt_u32_e64 s[20:21], v14, v15
	v_cmp_lt_u32_e64 s[22:23], v14, v16
	v_mov_b32_e32 v12, 0x2100
	v_mov_b32_e32 v14, 0x4200
	v_mov_b32_e32 v15, 0x6300
	v_mul_u32_u24_e32 v1, 0x210, v130
	v_mad_u32_u24 v12, v130, s42, v12
	v_mad_u32_u24 v14, v130, s42, v14
	v_mad_u32_u24 v15, v130, s42, v15
	v_add3_u32 v170, s38, v1, v164
	v_add3_u32 v171, s38, v12, v164
	v_add3_u32 v172, s38, v14, v164
	v_add3_u32 v173, s38, v15, v164
	s_add_i32 s38, 0, 0x10880
	v_add3_u32 v174, s38, v1, v164
	v_add3_u32 v175, s38, v12, v164
	v_add3_u32 v177, s38, v14, v164
	v_add3_u32 v178, s38, v15, v164
	s_add_i32 s38, 0, 0x108c0
	v_add3_u32 v179, s38, v1, v164
	v_add3_u32 v180, s38, v12, v164
	v_add3_u32 v181, s38, v14, v164
	v_add3_u32 v182, s38, v15, v164
	s_add_i32 s38, 0, 0x10900
	v_add3_u32 v183, s38, v1, v164
	v_add3_u32 v184, s38, v12, v164
	v_add3_u32 v185, s38, v14, v164
	v_add3_u32 v186, s38, v15, v164
	s_add_i32 s38, 0, 0x10940
	v_bfe_u32 v9, v176, 2, 2
	v_add3_u32 v187, s38, v1, v164
	v_add3_u32 v188, s38, v12, v164
	v_add3_u32 v189, s38, v14, v164
	v_add3_u32 v190, s38, v15, v164
	s_add_i32 s38, 0, 0x10980
	v_lshlrev_b32_e32 v0, 3, v224
	v_or_b32_e32 v9, v164, v9
	v_lshrrev_b32_e32 v134, 1, v176
	v_add3_u32 v191, s38, v1, v164
	v_add3_u32 v192, s38, v12, v164
	v_add3_u32 v193, s38, v14, v164
	v_add3_u32 v194, s38, v15, v164
	s_add_i32 s38, 0, 0x109c0
	v_add3_u32 v201, 0, v163, v7
	v_lshlrev_b32_e32 v7, 13, v130
	v_mov_b32_e32 v133, 0
	s_movk_i32 s4, 0x80
	v_add3_u32 v195, s38, v1, v164
	v_add3_u32 v196, s38, v12, v164
	v_add3_u32 v197, s38, v14, v164
	v_add3_u32 v198, s38, v15, v164
	v_mul_u32_u24_e32 v1, 0x90, v130
	v_mul_u32_u24_e32 v12, 0x110, v9
	v_lshl_or_b32 v138, v128, 13, v2
	v_or3_b32 v142, v7, v10, v164
	v_lshlrev_b32_e32 v7, 5, v134
	s_mov_b32 s38, 0x180000
	v_lshlrev_b32_e32 v146, 1, v0
	v_mbcnt_lo_u32_b32 v0, -1, 0
	s_mov_b32 s39, 0
	v_cmp_gt_u32_e64 s[4:5], s4, v176
	v_cmp_gt_u32_e64 s[6:7], 16, v128
	v_lshlrev_b32_e32 v166, 3, v130
	v_lshl_add_u64 v[136:137], s[0:1], 0, v[132:133]
	v_add_u32_e32 v168, 0x2100, v167
	v_mul_u32_u24_e32 v199, 0x210, v9
	v_add3_u32 v200, v11, v165, v12
	v_mov_b32_e32 v139, v133
	v_or_b32_e32 v140, 0xe300800, v138
	v_mov_b32_e32 v141, v133
	v_mov_b32_e32 v143, v133
	s_lshl_b32 s73, s2, 4
	s_lshl_b32 s74, s54, 4
	v_or3_b32 v144, v7, v132, s38
	v_mov_b32_e32 v145, v133
	s_mov_b64 s[42:43], 0x41000
	s_movk_i32 s75, 0x1000
	s_mov_b64 s[52:53], 0x80000
	s_mov_b32 s76, 0x80000
	s_mov_b64 s[54:55], 0x81000
	v_mbcnt_hi_u32_b32 v202, -1, v0
	s_mov_b64 s[56:57], 0x800
	v_lshlrev_b32_e32 v132, 1, v2
	v_lshlrev_b32_e32 v148, 1, v4
	v_add_u32_e32 v203, v8, v13
	v_add_u32_e32 v204, v6, v3
	v_add_u32_e32 v205, v5, v1
	s_mov_b32 s77, s2
	s_mov_b32 s78, s2
	v_lshrrev_b32_e32 v129, 5, v176
	v_mul_u32_u24_e32 v129, 0x210, v129
	v_and_b32_e32 v255, 31, v176
	v_lshl_add_u32 v129, v255, 4, v129
	v_mov_b32_e32 v131, v129
	v_add_u32_e32 v129, 0x10800, v129
	v_lshrrev_b32_e32 v135, 4, v176
	v_mul_u32_u24_e32 v135, 0x110, v135
	v_lshl_add_u32 v135, v130, 4, v135
	v_add_u32_e32 v135, 0x18c00, v135
	v_lshrrev_b32_e32 v146, 5, v176
	v_lshlrev_b32_e32 v255, 4, v255
	v_lshl_or_b32 v146, v146, 13, v255
	v_or_b32_e32 v140, 0xe300800, v146
	v_lshrrev_b32_e32 v138, 4, v176
	v_lshlrev_b32_e32 v255, 4, v130
	v_lshl_or_b32 v138, v138, 13, v255
	s_mov_b64 s[98:99], 0x20000
	s_mov_b64 s[100:101], 0x40000
	v_and_b32_e32 v255, 16, v176
	v_lshlrev_b32_e32 v255, 4, v255
	v_and_b32_e32 v0, 32, v176
	v_lshl_or_b32 v255, v0, 2, v255
	v_lshl_or_b32 v255, v130, 3, v255
	v_add_u32_e32 v255, 0x23800, v255
	v_lshrrev_b32_e32 v129, 5, v176
	v_mul_u32_u24_e32 v129, 0x210, v129
	v_and_b32_e32 v0, 28, v176
	v_lshl_add_u32 v129, v0, 4, v129
	v_and_b32_e32 v0, 1, v176
	v_lshl_add_u32 v129, v0, 5, v129
	v_and_b32_e32 v0, 2, v176
	v_lshl_add_u32 v129, v0, 2, v129
	v_add_u32_e32 v129, 0x10800, v129
	v_mul_u32_u24_e32 v170, 0x210, v130
	v_lshl_add_u32 v170, v164, 1, v170
	v_add_u32_e32 v170, 0x10800, v170
	v_add_u32_e32 v201, 0x8400, v163
	v_add_u32_e32 v201, v201, v164
	s_branch .LBB0_1133

; #define LDS_BAR() do { asm volatile("s_waitcnt lgkmcnt(0)" ::: "memory"); __builtin_amdgcn_s_barrier(); asm volatile("" ::: "memory"); } while (0)
; #define RET_STAGE(Kd, Vd) do { _Pragma("unroll") for (int uu = 0; uu < 4; ++uu) { const int c8 = lc8 + 8 * uu; *(LAS u32x4*)(Ql + ls * 264 + 8 * c8) = pq[uu]; *(LAS u32x4*)((Kd) + ls * 264 + 8 * c8) = pkv[uu]; } \
;         _Pragma("unroll") for (int uu = 0; uu < 2; ++uu) { const int c8 = lc8 + 8 * uu; *(LAS u32x4*)((Vd) + ls * 136 + 8 * c8) = pv[uu]; } } while (0)
; __device__ __forceinline__ void ret_unit(LAS unsigned char* lds, bf16_t* QKV, float* gn, int b, int h, int vs, bool commit, const float* s00p, const float* ss3, bool skel = false) {
;     ...
;     RET_LOAD(0);
;     LDS_BAR();
;     RET_STAGE(Kb, Vb);
;     RET_LOAD(1);
;     if (tid < 128) st[tid] = 0.f;
;     LDS_BAR();
.LBB0_1133:
	s_ashr_i32 s58, s78, 2
	s_and_b32 s38, s78, 4
	s_and_b32 s58, s58, -8
	s_or_b32 s38, s58, s38
	s_and_b32 s79, s78, 3
	s_or_b32 s58, s38, s79
	s_ashr_i32 s59, s58, 31
	s_ashr_i32 s64, s38, 2
	s_lshl_b64 s[58:59], s[58:59], 2
	s_add_u32 s62, s3, s58
	s_addc_u32 s63, s72, s59
	s_ashr_i32 s65, s64, 31
	s_lshl_b64 s[58:59], s[64:65], 11
	s_lshl_b64 s[68:69], s[64:65], 13
	s_add_u32 s68, s33, s68
	v_mov_b32_e32 v3, s59
	v_mov_b32_e32 v2, s58
	s_addc_u32 s69, s70, s69
	global_load_dword v0, v133, s[62:63]
	global_load_dword v1, v133, s[68:69]
	v_lshlrev_b64 v[2:3], 13, v[2:3]
	s_lshl_b32 s62, s78, 4
	v_lshl_add_u64 v[34:35], s[26:27], 0, v[2:3]
	s_lshl_b32 s38, s79, 9
	s_lshl_b32 s68, s79, 10
	s_mov_b32 s69, s39
	s_and_b32 s62, s62, 0x180
	v_lshl_add_u64 v[2:3], v[34:35], 0, s[38:39]
	s_lshl_b32 s62, s62, 1
	s_mov_b32 s63, s39
	v_lshl_add_u64 v[34:35], v[34:35], 0, s[68:69]
	v_mov_b32_e32 v147, v133
	v_lshl_add_u64 v[34:35], v[34:35], 0, s[62:63]
	v_lshl_add_u64 v[44:45], v[34:35], 0, v[138:139]
	v_add_co_u32_e32 v34, vcc, s75, v44
	v_lshl_add_u64 v[42:43], v[2:3], 0, v[146:147]
	v_lshl_add_u64 v[38:39], v[44:45], 0, s[42:43]
	v_addc_co_u32_e32 v35, vcc, 0, v45, vcc
	s_waitcnt lgkmcnt(0)
	v_lshl_add_u64 v[14:15], v[42:43], 0, s[98:99]
	v_lshl_add_u64 v[26:27], v[14:15], 0, s[98:99]
	v_lshl_add_u64 v[30:31], v[26:27], 0, s[98:99]
	global_load_dwordx4 v[2:5], v[42:43], off
	global_load_dwordx4 v[6:9], v[14:15], off
	global_load_dwordx4 v[10:13], v[42:43], off offset:2048
	global_load_dwordx4 v[14:17], v[14:15], off offset:2048
	global_load_dwordx4 v[18:21], v[26:27], off
	global_load_dwordx4 v[22:25], v[30:31], off
	global_load_dwordx4 v[26:29], v[26:27], off offset:2048
	global_load_dwordx4 v[30:33], v[30:31], off offset:2048
	global_load_dwordx4 v[34:37], v[34:35], off
	global_load_dwordx4 v[38:41], v[38:39], off
	s_waitcnt lgkmcnt(0)
	s_barrier
	v_lshl_add_u64 v[80:81], v[42:43], 0, s[52:53]
	v_lshl_add_u64 v[76:77], v[80:81], 0, s[98:99]
	v_lshl_add_u64 v[84:85], v[76:77], 0, s[98:99]
	v_lshl_add_u64 v[92:93], v[84:85], 0, s[98:99]
	global_load_dwordx4 v[64:67], v[76:77], off
	global_load_dwordx4 v[68:71], v[84:85], off
	global_load_dwordx4 v[72:75], v[80:81], off
	global_load_dwordx4 v[88:91], v[92:93], off
	global_load_dwordx4 v[76:79], v[76:77], off offset:2048
	global_load_dwordx4 v[84:87], v[84:85], off offset:2048
	global_load_dwordx4 v[80:83], v[80:81], off offset:2048
	global_load_dwordx4 v[92:95], v[92:93], off offset:2048
	v_lshl_add_u64 v[98:99], v[44:45], 0, s[54:55]
	v_lshl_add_u64 v[100:101], v[98:99], 0, s[100:101]
	global_load_dwordx4 v[96:99], v[98:99], off
	global_load_dwordx4 v[100:103], v[100:101], off
	s_waitcnt vmcnt(19)
	ds_write_b64 v129, v[2:3]
	ds_write_b64 v129, v[4:5] offset:16
	s_waitcnt vmcnt(17)
	ds_write_b128 v131, v[10:13]
	ds_write_b64 v129, v[6:7] offset:8448
	ds_write_b64 v129, v[8:9] offset:8464
	s_waitcnt vmcnt(16)
	ds_write_b128 v131, v[14:17] offset:8448
	s_waitcnt vmcnt(15)
	ds_write_b64 v129, v[18:19] offset:16896
	ds_write_b64 v129, v[20:21] offset:16912
	s_waitcnt vmcnt(13)
	ds_write_b128 v131, v[26:29] offset:16896
	ds_write_b64 v129, v[22:23] offset:25344
	ds_write_b64 v129, v[24:25] offset:25360
	s_waitcnt vmcnt(12)
	ds_write_b128 v131, v[30:33] offset:25344
	s_waitcnt vmcnt(11)
	ds_write_b128 v135, v[34:37]
	s_waitcnt vmcnt(10)
	ds_write_b128 v135, v[38:41] offset:8704
	s_and_saveexec_b64 s[68:69], s[4:5]
	ds_write_b32 v162, v133
	s_or_b64 exec, exec, s[68:69]
	v_cvt_f32_ubyte0_e32 v2, s79
	v_sub_f32_e32 v2, 0xc0a00000, v2
	v_exp_f32_e32 v2, v2
	v_mov_b32_e32 v3, 0x358637bd
	v_fmamk_f32 v1, v1, 0x3a800000, v3
	v_rsq_f32_e32 v1, v1
	v_sub_f32_e32 v2, 1.0, v2
	v_log_f32_e32 v2, v2
	s_and_b32 s63, s77, 3
	s_lshl_b32 s68, s73, 1
	s_lshl_b32 s80, s63, 9
	v_mul_f32_e32 v2, 0x42800000, v2
	s_and_b32 s83, s68, 0x300
	v_exp_f32_e32 v150, v2
	s_lshl_b64 s[68:69], s[64:65], 24
	s_lshl_b32 s82, s63, 10
	s_or_b32 s80, s68, s80
	s_mov_b32 s81, s69
	s_lshl_b32 s63, s63, 3
	v_mul_f32_e32 v0, v0, v1
	s_waitcnt lgkmcnt(0)
	s_barrier
	v_lshl_add_u64 v[154:155], s[80:81], 0, v[140:141]
	s_or_b32 s80, s83, s82
	s_lshl_b64 s[64:65], s[64:65], 16
	v_mul_f32_e32 v0, v1, v0
	s_or_b32 s68, s68, s80
	s_or_b32 s64, s64, s63
	v_mov_b32_e32 v40, 0
	v_mul_f32_e32 v147, 0x3d800000, v0
	v_mov_b32_e32 v152, v150
	v_mov_b32_e32 v153, v150
	v_lshl_add_u64 v[156:157], s[68:69], 0, v[142:143]
	v_lshl_add_u64 v[158:159], s[64:65], 0, v[144:145]
	v_lshl_add_u64 v[160:161], s[68:69], 0, v[138:139]
	s_mov_b32 s63, 0
	v_mov_b32_e32 v41, v40
	v_mov_b32_e32 v42, v40
	v_mov_b32_e32 v43, v40
	v_mov_b32_e32 v44, v40
	v_mov_b32_e32 v45, v40
	v_mov_b32_e32 v46, v40
	v_mov_b32_e32 v47, v40
	v_mov_b32_e32 v48, v40
	v_mov_b32_e32 v49, v40
	v_mov_b32_e32 v50, v40
	v_mov_b32_e32 v51, v40
	v_mov_b32_e32 v52, v40
	v_mov_b32_e32 v53, v40
	v_mov_b32_e32 v54, v40
	v_mov_b32_e32 v55, v40
	v_mov_b32_e32 v56, v40
	v_mov_b32_e32 v57, v40
	v_mov_b32_e32 v58, v40
	v_mov_b32_e32 v59, v40
	v_mov_b32_e32 v60, v40
	v_mov_b32_e32 v61, v40
	v_mov_b32_e32 v62, v40
	v_mov_b32_e32 v63, v40
	v_mov_b32_e32 v36, v40
	v_mov_b32_e32 v37, v40
	v_mov_b32_e32 v38, v40
	v_mov_b32_e32 v39, v40
	v_mov_b32_e32 v32, v40
	v_mov_b32_e32 v33, v40
	v_mov_b32_e32 v34, v40
	v_mov_b32_e32 v35, v40
	v_mov_b32_e32 v28, v40
	v_mov_b32_e32 v29, v40
	v_mov_b32_e32 v30, v40
	v_mov_b32_e32 v31, v40
	v_mov_b32_e32 v24, v40
	v_mov_b32_e32 v25, v40
	v_mov_b32_e32 v26, v40
	v_mov_b32_e32 v27, v40
	v_mov_b32_e32 v20, v40
	v_mov_b32_e32 v21, v40
	v_mov_b32_e32 v22, v40
	v_mov_b32_e32 v23, v40
	v_mov_b32_e32 v16, v40
	v_mov_b32_e32 v17, v40
	v_mov_b32_e32 v18, v40
	v_mov_b32_e32 v19, v40
	v_mov_b32_e32 v12, v40
	v_mov_b32_e32 v13, v40
	v_mov_b32_e32 v14, v40
	v_mov_b32_e32 v15, v40
	v_mov_b32_e32 v8, v40
	v_mov_b32_e32 v9, v40
	v_mov_b32_e32 v10, v40
	v_mov_b32_e32 v11, v40
	v_mov_b32_e32 v4, v40
	v_mov_b32_e32 v5, v40
	v_mov_b32_e32 v6, v40
	v_mov_b32_e32 v7, v40
	v_mov_b32_e32 v0, v40
	v_mov_b32_e32 v1, v40
	v_mov_b32_e32 v2, v40
	v_mov_b32_e32 v3, v40
	s_waitcnt vmcnt(0)
	s_branch .LBB0_1137

; #define LAS __attribute__((address_space(3)))
; __device__ __forceinline__ u32x2 pack4(f32x4 v) { return (u32x2){pk2(v[0], v[1]), pk2(v[2], v[3])}; }
; #define SB0 __builtin_amdgcn_sched_barrier(0)
; #define SB0 __builtin_amdgcn_sched_barrier(0)
; #define RA_LOAD(ks_) do { ka[(ks_) % 3] = *(const LAS bf16x8*)(Kl + (16 * si + fr) * 264 + 32 * (ks_) + 8 * fq); \
;               _Pragma("unroll") for (int tt = 0; tt < 2; ++tt) qb[(ks_) % 3][tt] = *(const LAS bf16x8*)(Ql + (16 * (ti0 + tt) + fr) * 264 + 32 * (ks_) + 8 * fq); } while (0)
; __device__ __forceinline__ void ret_unit(LAS unsigned char* lds, bf16_t* QKV, float* gn, int b, int h, int vs, bool commit, const float* s00p, const float* ss3, bool skel = false) {
;     ...
;         { f32x4 sv[2] = {(f32x4){0.f, 0.f, 0.f, 0.f}, (f32x4){0.f, 0.f, 0.f, 0.f}};
;           bf16x8 ka[3], qb[3][2];
;     ...
;           RA_LOAD(0); RA_LOAD(1); SB0;
; #pragma unroll
;           for (int ks = 0; ks < 8; ++ks) { if (ks + 2 < 8) RA_LOAD(ks + 2); SB0;
; #pragma unroll
;               for (int tt = 0; tt < 2; ++tt) sv[tt] = __builtin_amdgcn_mfma_f32_16x16x32_bf16(ka[ks % 3], qb[ks % 3][tt], sv[tt], 0, 0, 0);
;               SB0; }
;     ...
; #pragma unroll
;           for (int tt = 0; tt < 2; ++tt) { const int t = 16 * (ti0 + tt) + fr; f32x4 pvv;
; #pragma unroll
;               for (int r = 0; r < 4; ++r) { const int sidx = 16 * si + 4 * fq + r; pvv[r] = t >= sidx ? sv[tt][r] : 0.f; }
;               if (c == 0 && t == 0 && si == 0 && fq == 0) pvv[0] = s00;
;               *(LAS u32x2*)(Pl + t * 72 + 16 * si + 4 * fq) = pack4(pvv); } }
;         { u32x4 qf[3][4];
;     ...
;           RC_LOAD(0); RC_LOAD(1); SB0;
; #pragma unroll
;           for (int kk = 0; kk < 8; ++kk) { if (kk + 2 < 8) RC_LOAD(kk + 2);
;               const u32x2 s0 = pack4(state[2 * kk]), s1 = pack4(state[2 * kk + 1]);
;               const u32x4 aw = (u32x4){s0.x, s0.y, s1.x, s1.y}; const bf16x8 afrag = __builtin_bit_cast(bf16x8, aw);
;               SB0;
; #pragma unroll
;               for (int n = 0; n < 4; ++n) oacc[n] = __builtin_amdgcn_mfma_f32_16x16x32_bf16(afrag, __builtin_bit_cast(bf16x8, qf[kk % 3][n]), oacc[n], 0, 0, 0);
;               SB0; }
.LBB0_1137:
	s_and_b32 s65, s63, 1
	s_mul_i32 s64, s65, 0x8400
	s_add_i32 s64, s64, 0
	v_lshlrev_b32_e32 v104, 1, v164
	v_add3_u32 v149, s64, v163, v164
	ds_read_b128 v[104:107], v203
	s_waitcnt lgkmcnt(1)
	ds_read_b128 v[108:111], v203 offset:8448
	ds_read2_b64 v[112:115], v149 offset1:4
	ds_read2_b64 v[116:119], v149 offset0:8 offset1:12
	ds_read_b128 v[120:123], v167 offset:64
	ds_read_b128 v[124:127], v168 offset:64
	ds_read2_b64 v[206:209], v149 offset0:16 offset1:20
	ds_read_b128 v[210:213], v203 offset:128
	ds_read_b128 v[214:217], v203 offset:8576
	s_waitcnt lgkmcnt(6)
	v_mfma_f32_16x16x32_bf16 v[104:107], v[112:115], v[104:107], 0
	v_mfma_f32_16x16x32_bf16 v[108:111], v[112:115], v[108:111], 0
	ds_read2_b64 v[112:115], v149 offset0:24 offset1:28
	ds_read_b128 v[218:221], v203 offset:192
	ds_read_b128 v[222:225], v203 offset:8640
	s_waitcnt lgkmcnt(7)
	v_mfma_f32_16x16x32_bf16 v[104:107], v[116:119], v[120:123], v[104:107]
	s_waitcnt lgkmcnt(6)
	v_mfma_f32_16x16x32_bf16 v[108:111], v[116:119], v[124:127], v[108:111]
	ds_read2_b64 v[116:119], v149 offset0:32 offset1:36
	ds_read_b128 v[120:123], v203 offset:256
	ds_read_b128 v[124:127], v203 offset:8704
	s_waitcnt lgkmcnt(7)
	v_mfma_f32_16x16x32_bf16 v[104:107], v[206:209], v[210:213], v[104:107]
	s_waitcnt lgkmcnt(6)
	v_mfma_f32_16x16x32_bf16 v[108:111], v[206:209], v[214:217], v[108:111]
	ds_read2_b64 v[206:209], v149 offset0:40 offset1:44
	ds_read_b128 v[210:213], v203 offset:320
	ds_read_b128 v[214:217], v203 offset:8768
	s_waitcnt lgkmcnt(7)
	v_mfma_f32_16x16x32_bf16 v[104:107], v[112:115], v[218:221], v[104:107]
	s_waitcnt lgkmcnt(6)
	v_mfma_f32_16x16x32_bf16 v[108:111], v[112:115], v[222:225], v[108:111]
	ds_read2_b64 v[112:115], v149 offset0:48 offset1:52
	ds_read_b128 v[218:221], v203 offset:384
	ds_read_b128 v[222:225], v203 offset:8832
	s_waitcnt lgkmcnt(7)
	v_mfma_f32_16x16x32_bf16 v[104:107], v[116:119], v[120:123], v[104:107]
	s_waitcnt lgkmcnt(6)
	v_mfma_f32_16x16x32_bf16 v[108:111], v[116:119], v[124:127], v[108:111]
	ds_read2_b64 v[116:119], v149 offset0:56 offset1:60
	ds_read_b128 v[120:123], v203 offset:448
	ds_read_b128 v[124:127], v203 offset:8896
	s_waitcnt lgkmcnt(7)
	v_mfma_f32_16x16x32_bf16 v[104:107], v[206:209], v[210:213], v[104:107]
	s_waitcnt lgkmcnt(6)
	v_mfma_f32_16x16x32_bf16 v[108:111], v[206:209], v[214:217], v[108:111]
	s_waitcnt lgkmcnt(4)
	v_mfma_f32_16x16x32_bf16 v[104:107], v[112:115], v[218:221], v[104:107]
	s_waitcnt lgkmcnt(3)
	v_mfma_f32_16x16x32_bf16 v[108:111], v[112:115], v[222:225], v[108:111]
	s_waitcnt lgkmcnt(1)
	v_mfma_f32_16x16x32_bf16 v[104:107], v[116:119], v[120:123], v[104:107]
	s_waitcnt lgkmcnt(0)
	v_mfma_f32_16x16x32_bf16 v[108:111], v[116:119], v[124:127], v[108:111]
	v_or_b32_e32 v112, s63, v169
	v_cmp_eq_u32_e32 vcc, 0, v112
	s_nop 3
	v_cndmask_b32_e64 v104, v104, 0, s[8:9]
	s_and_b64 vcc, vcc, s[6:7]
	v_cndmask_b32_e64 v105, 0, v105, s[10:11]
	v_cndmask_b32_e32 v104, v104, v147, vcc
	v_cndmask_b32_e64 v106, v106, 0, s[12:13]
	v_cndmask_b32_e64 v107, v107, 0, s[14:15]
	v_cvt_pk_bf16_f32 v104, v104, v105
	v_cvt_pk_bf16_f32 v105, v106, v107
	ds_write_b64 v204, v[104:105]
	v_cndmask_b32_e64 v104, v108, 0, s[16:17]
	v_cndmask_b32_e64 v105, 0, v109, s[18:19]
	v_cndmask_b32_e64 v106, v110, 0, s[20:21]
	v_cndmask_b32_e64 v107, v111, 0, s[22:23]
	v_cvt_pk_bf16_f32 v104, v104, v105
	v_cvt_pk_bf16_f32 v105, v106, v107
	ds_write_b64 v204, v[104:105] offset:2304
	ds_read_b128 v[104:107], v170
	ds_read_b128 v[108:111], v170 offset:8448
	ds_read_b128 v[112:115], v170 offset:16896
	ds_read_b128 v[116:119], v170 offset:25344
	ds_read_b128 v[120:123], v170 offset:64
	ds_read_b128 v[124:127], v170 offset:8512
	ds_read_b128 v[206:209], v170 offset:16960
	ds_read_b128 v[210:213], v170 offset:25408
	ds_read_b128 v[214:217], v170 offset:128
	ds_read_b128 v[218:221], v170 offset:8576
	ds_read_b128 v[222:225], v170 offset:17024
	ds_read_b128 v[226:229], v170 offset:25472
	v_cvt_pk_bf16_f32 v230, v60, v61
	v_cvt_pk_bf16_f32 v231, v62, v63
	v_cvt_pk_bf16_f32 v232, v56, v57
	v_cvt_pk_bf16_f32 v233, v58, v59
	s_waitcnt lgkmcnt(11)
	v_mfma_f32_16x16x32_bf16 v[104:107], v[230:233], v[104:107], 0
	s_waitcnt lgkmcnt(10)
	v_mfma_f32_16x16x32_bf16 v[108:111], v[230:233], v[108:111], 0
	s_waitcnt lgkmcnt(9)
	v_mfma_f32_16x16x32_bf16 v[112:115], v[230:233], v[112:115], 0
	s_waitcnt lgkmcnt(8)
	v_mfma_f32_16x16x32_bf16 v[116:119], v[230:233], v[116:119], 0
	ds_read_b128 v[230:233], v170 offset:192
	ds_read_b128 v[234:237], v170 offset:8640
	ds_read_b128 v[238:241], v170 offset:17088
	ds_read_b128 v[242:245], v170 offset:25536
	v_cvt_pk_bf16_f32 v246, v52, v53
	v_cvt_pk_bf16_f32 v247, v54, v55
	v_cvt_pk_bf16_f32 v248, v48, v49
	v_cvt_pk_bf16_f32 v249, v50, v51
	s_waitcnt lgkmcnt(11)
	v_mfma_f32_16x16x32_bf16 v[104:107], v[246:249], v[120:123], v[104:107]
	s_waitcnt lgkmcnt(10)
	v_mfma_f32_16x16x32_bf16 v[108:111], v[246:249], v[124:127], v[108:111]
	s_waitcnt lgkmcnt(9)
	v_mfma_f32_16x16x32_bf16 v[112:115], v[246:249], v[206:209], v[112:115]
	s_waitcnt lgkmcnt(8)
	v_mfma_f32_16x16x32_bf16 v[116:119], v[246:249], v[210:213], v[116:119]
	ds_read_b128 v[120:123], v170 offset:256
	ds_read_b128 v[124:127], v170 offset:8704
	ds_read_b128 v[206:209], v170 offset:17152
	ds_read_b128 v[210:213], v170 offset:25600
	v_cvt_pk_bf16_f32 v246, v44, v45
	v_cvt_pk_bf16_f32 v247, v46, v47
	v_cvt_pk_bf16_f32 v248, v40, v41
	v_cvt_pk_bf16_f32 v249, v42, v43
	s_waitcnt lgkmcnt(11)
; __device__ __forceinline__ u32x2 pack4(f32x4 v) { return (u32x2){pk2(v[0], v[1]), pk2(v[2], v[3])}; }
; #define LDS_BAR() do { asm volatile("s_waitcnt lgkmcnt(0)" ::: "memory"); __builtin_amdgcn_s_barrier(); asm volatile("" ::: "memory"); } while (0)
; #define SB0 __builtin_amdgcn_sched_barrier(0)
; #define RET_STAGE(Kd, Vd) do { _Pragma("unroll") for (int uu = 0; uu < 4; ++uu) { const int c8 = lc8 + 8 * uu; *(LAS u32x4*)(Ql + ls * 264 + 8 * c8) = pq[uu]; *(LAS u32x4*)((Kd) + ls * 264 + 8 * c8) = pkv[uu]; } \
;         _Pragma("unroll") for (int uu = 0; uu < 2; ++uu) { const int c8 = lc8 + 8 * uu; *(LAS u32x4*)((Vd) + ls * 136 + 8 * c8) = pv[uu]; } } while (0)
; #define SB0 __builtin_amdgcn_sched_barrier(0)
; #define RC_LOAD(kk_) do { _Pragma("unroll") for (int n = 0; n < 4; ++n) { const u32x2 lo = *(const LAS u32x2*)(Ql + (16 * n + fr) * 264 + 32 * (kk_) + 4 * fq), hi = *(const LAS u32x2*)(Ql + (16 * n + fr) * 264 + 32 * (kk_) + 16 + 4 * fq); \
;               qf[(kk_) % 3][n] = (u32x4){lo.x, lo.y, hi.x, hi.y}; } } while (0)
; __device__ __forceinline__ void ret_unit(LAS unsigned char* lds, bf16_t* QKV, float* gn, int b, int h, int vs, bool commit, const float* s00p, const float* ss3, bool skel = false) {
;     ...
;           RC_LOAD(0); RC_LOAD(1); SB0;
; #pragma unroll
;           for (int kk = 0; kk < 8; ++kk) { if (kk + 2 < 8) RC_LOAD(kk + 2);
;               const u32x2 s0 = pack4(state[2 * kk]), s1 = pack4(state[2 * kk + 1]);
;               const u32x4 aw = (u32x4){s0.x, s0.y, s1.x, s1.y}; const bf16x8 afrag = __builtin_bit_cast(bf16x8, aw);
;               SB0;
; #pragma unroll
;               for (int n = 0; n < 4; ++n) oacc[n] = __builtin_amdgcn_mfma_f32_16x16x32_bf16(afrag, __builtin_bit_cast(bf16x8, qf[kk % 3][n]), oacc[n], 0, 0, 0);
;               SB0; }
;     ...
;         }
; #pragma unroll
;         for (int n = 0; n < 4; ++n) oacc[n] = oacc[n] * cd;
;         }
;         LDS_BAR();
;         if (c + 1 < 32) { RET_STAGE(Kn, Vn); if (c + 2 < 32) RET_LOAD(c + 2); }
	v_mfma_f32_16x16x32_bf16 v[104:107], v[246:249], v[214:217], v[104:107]
	s_waitcnt lgkmcnt(10)
	v_mfma_f32_16x16x32_bf16 v[108:111], v[246:249], v[218:221], v[108:111]
	s_waitcnt lgkmcnt(9)
	v_mfma_f32_16x16x32_bf16 v[112:115], v[246:249], v[222:225], v[112:115]
	s_waitcnt lgkmcnt(8)
	v_mfma_f32_16x16x32_bf16 v[116:119], v[246:249], v[226:229], v[116:119]
	ds_read_b128 v[214:217], v170 offset:320
	ds_read_b128 v[218:221], v170 offset:8768
	ds_read_b128 v[222:225], v170 offset:17216
	ds_read_b128 v[226:229], v170 offset:25664
	v_cvt_pk_bf16_f32 v246, v36, v37
	v_cvt_pk_bf16_f32 v247, v38, v39
	v_cvt_pk_bf16_f32 v248, v32, v33
	v_cvt_pk_bf16_f32 v249, v34, v35
	s_waitcnt lgkmcnt(11)
	v_mfma_f32_16x16x32_bf16 v[104:107], v[246:249], v[230:233], v[104:107]
	s_waitcnt lgkmcnt(10)
	v_mfma_f32_16x16x32_bf16 v[108:111], v[246:249], v[234:237], v[108:111]
	s_waitcnt lgkmcnt(9)
	v_mfma_f32_16x16x32_bf16 v[112:115], v[246:249], v[238:241], v[112:115]
	s_waitcnt lgkmcnt(8)
	v_mfma_f32_16x16x32_bf16 v[116:119], v[246:249], v[242:245], v[116:119]
	ds_read_b128 v[230:233], v170 offset:384
	ds_read_b128 v[234:237], v170 offset:8832
	ds_read_b128 v[238:241], v170 offset:17280
	ds_read_b128 v[242:245], v170 offset:25728
	v_cvt_pk_bf16_f32 v246, v28, v29
	v_cvt_pk_bf16_f32 v247, v30, v31
	v_cvt_pk_bf16_f32 v248, v24, v25
	v_cvt_pk_bf16_f32 v249, v26, v27
	s_waitcnt lgkmcnt(11)
	v_mfma_f32_16x16x32_bf16 v[104:107], v[246:249], v[120:123], v[104:107]
	s_waitcnt lgkmcnt(10)
	v_mfma_f32_16x16x32_bf16 v[108:111], v[246:249], v[124:127], v[108:111]
	s_waitcnt lgkmcnt(9)
	v_mfma_f32_16x16x32_bf16 v[112:115], v[246:249], v[206:209], v[112:115]
	s_waitcnt lgkmcnt(8)
	v_mfma_f32_16x16x32_bf16 v[116:119], v[246:249], v[210:213], v[116:119]
	ds_read_b128 v[120:123], v170 offset:448
	ds_read_b128 v[124:127], v170 offset:8896
	ds_read_b128 v[206:209], v170 offset:17344
	ds_read_b128 v[210:213], v170 offset:25792
	v_cvt_pk_bf16_f32 v246, v20, v21
	v_cvt_pk_bf16_f32 v247, v22, v23
	v_cvt_pk_bf16_f32 v248, v16, v17
	v_cvt_pk_bf16_f32 v249, v18, v19
	s_waitcnt lgkmcnt(11)
	v_mfma_f32_16x16x32_bf16 v[104:107], v[246:249], v[214:217], v[104:107]
	s_waitcnt lgkmcnt(10)
	v_mfma_f32_16x16x32_bf16 v[108:111], v[246:249], v[218:221], v[108:111]
	s_waitcnt lgkmcnt(9)
	v_mfma_f32_16x16x32_bf16 v[112:115], v[246:249], v[222:225], v[112:115]
	s_waitcnt lgkmcnt(8)
	v_mfma_f32_16x16x32_bf16 v[116:119], v[246:249], v[226:229], v[116:119]
	v_cvt_pk_bf16_f32 v214, v12, v13
	v_cvt_pk_bf16_f32 v215, v14, v15
	v_cvt_pk_bf16_f32 v216, v8, v9
	v_cvt_pk_bf16_f32 v217, v10, v11
	s_waitcnt lgkmcnt(7)
	v_mfma_f32_16x16x32_bf16 v[104:107], v[214:217], v[230:233], v[104:107]
	s_waitcnt lgkmcnt(6)
	v_mfma_f32_16x16x32_bf16 v[108:111], v[214:217], v[234:237], v[108:111]
	s_waitcnt lgkmcnt(5)
	v_mfma_f32_16x16x32_bf16 v[218:221], v[214:217], v[238:241], v[112:115]
	s_waitcnt lgkmcnt(4)
	v_mfma_f32_16x16x32_bf16 v[214:217], v[214:217], v[242:245], v[116:119]
	v_cvt_pk_bf16_f32 v222, v4, v5
	v_cvt_pk_bf16_f32 v223, v6, v7
	v_cvt_pk_bf16_f32 v224, v0, v1
	v_cvt_pk_bf16_f32 v225, v2, v3
	s_waitcnt lgkmcnt(3)
	v_mfma_f32_16x16x32_bf16 v[116:119], v[222:225], v[120:123], v[104:107]
	s_waitcnt lgkmcnt(2)
	v_mfma_f32_16x16x32_bf16 v[112:115], v[222:225], v[124:127], v[108:111]
	s_waitcnt lgkmcnt(1)
	v_mfma_f32_16x16x32_bf16 v[108:111], v[222:225], v[206:209], v[218:221]
	s_waitcnt lgkmcnt(0)
	v_mfma_f32_16x16x32_bf16 v[104:107], v[222:225], v[210:213], v[214:217]
	s_xor_b32 s68, s65, 1
	s_waitcnt lgkmcnt(0)
	s_barrier
	s_mul_i32 s69, s68, 0x8400
	s_mulk_i32 s68, 0x4400
	v_add_u32_e32 v120, s69, v131
	s_waitcnt vmcnt(7)
	ds_write_b64 v129, v[72:73]
	ds_write_b64 v129, v[74:75] offset:16
	ds_write_b128 v120, v[80:83]
	ds_write_b64 v129, v[64:65] offset:8448
	ds_write_b64 v129, v[66:67] offset:8464
	ds_write_b128 v120, v[76:79] offset:8448
	ds_write_b64 v129, v[68:69] offset:16896
	ds_write_b64 v129, v[70:71] offset:16912
	ds_write_b128 v120, v[84:87] offset:16896
	ds_write_b64 v129, v[88:89] offset:25344
	ds_write_b64 v129, v[90:91] offset:25360
	s_waitcnt vmcnt(6)
	ds_write_b128 v120, v[92:95] offset:25344
	v_add_u32_e32 v120, s68, v135
	s_cmp_gt_u32 s63, 29
	s_waitcnt vmcnt(5)
	ds_write_b128 v120, v[96:99]
	s_waitcnt vmcnt(4)
	ds_write_b128 v120, v[100:103] offset:8704
	s_cbranch_scc1 .LBB0_1139
	v_lshl_add_u64 v[80:81], s[50:51], 0, v[154:155]
	v_lshl_add_u64 v[76:77], v[80:81], 0, s[98:99]
	v_lshl_add_u64 v[84:85], v[76:77], 0, s[98:99]
	v_lshl_add_u64 v[92:93], v[84:85], 0, s[98:99]
	global_load_dwordx4 v[72:75], v[80:81], off offset:-2048
	global_load_dwordx4 v[64:67], v[76:77], off offset:-2048
	global_load_dwordx4 v[80:83], v[80:81], off
	global_load_dwordx4 v[76:79], v[76:77], off
	global_load_dwordx4 v[68:71], v[84:85], off offset:-2048
	global_load_dwordx4 v[88:91], v[92:93], off offset:-2048
	global_load_dwordx4 v[84:87], v[84:85], off
	global_load_dwordx4 v[92:95], v[92:93], off
	v_lshl_add_u64 v[96:97], s[50:51], 0, v[160:161]
	v_add_co_u32_e32 v98, vcc, 0xe301000, v96
	s_nop 1
	v_addc_co_u32_e32 v99, vcc, 0, v97, vcc
	v_lshl_add_u64 v[100:101], v[98:99], 0, s[100:101]
	global_load_dwordx4 v[96:99], v[98:99], off
	global_load_dwordx4 v[100:103], v[100:101], off

; #define LAS __attribute__((address_space(3)))
; __device__ __forceinline__ u32x2 pack4(f32x4 v) { return (u32x2){pk2(v[0], v[1]), pk2(v[2], v[3])}; }
; #define SB0 __builtin_amdgcn_sched_barrier(0)
; #define SB0 __builtin_amdgcn_sched_barrier(0)
; #define RA_LOAD(ks_) do { ka[(ks_) % 3] = *(const LAS bf16x8*)(Kl + (16 * si + fr) * 264 + 32 * (ks_) + 8 * fq); \
;               _Pragma("unroll") for (int tt = 0; tt < 2; ++tt) qb[(ks_) % 3][tt] = *(const LAS bf16x8*)(Ql + (16 * (ti0 + tt) + fr) * 264 + 32 * (ks_) + 8 * fq); } while (0)
; __device__ __forceinline__ void ret_unit(LAS unsigned char* lds, bf16_t* QKV, float* gn, int b, int h, int vs, bool commit, const float* s00p, const float* ss3, bool skel = false) {
;     ...
;         { f32x4 sv[2] = {(f32x4){0.f, 0.f, 0.f, 0.f}, (f32x4){0.f, 0.f, 0.f, 0.f}};
;           bf16x8 ka[3], qb[3][2];
;     ...
;           RA_LOAD(0); RA_LOAD(1); SB0;
; #pragma unroll
;           for (int ks = 0; ks < 8; ++ks) { if (ks + 2 < 8) RA_LOAD(ks + 2); SB0;
; #pragma unroll
;               for (int tt = 0; tt < 2; ++tt) sv[tt] = __builtin_amdgcn_mfma_f32_16x16x32_bf16(ka[ks % 3], qb[ks % 3][tt], sv[tt], 0, 0, 0);
;               SB0; }
;     ...
; #pragma unroll
;           for (int tt = 0; tt < 2; ++tt) { const int t = 16 * (ti0 + tt) + fr; f32x4 pvv;
; #pragma unroll
;               for (int r = 0; r < 4; ++r) { const int sidx = 16 * si + 4 * fq + r; pvv[r] = t >= sidx ? sv[tt][r] : 0.f; }
;               if (c == 0 && t == 0 && si == 0 && fq == 0) pvv[0] = s00;
;               *(LAS u32x2*)(Pl + t * 72 + 16 * si + 4 * fq) = pack4(pvv); } }
;         { u32x4 qf[3][4];
;     ...
;           RC_LOAD(0); RC_LOAD(1); SB0;
; #pragma unroll
;           for (int kk = 0; kk < 8; ++kk) { if (kk + 2 < 8) RC_LOAD(kk + 2);
;               const u32x2 s0 = pack4(state[2 * kk]), s1 = pack4(state[2 * kk + 1]);
;               const u32x4 aw = (u32x4){s0.x, s0.y, s1.x, s1.y}; const bf16x8 afrag = __builtin_bit_cast(bf16x8, aw);
;               SB0;
; #pragma unroll
;               for (int n = 0; n < 4; ++n) oacc[n] = __builtin_amdgcn_mfma_f32_16x16x32_bf16(afrag, __builtin_bit_cast(bf16x8, qf[kk % 3][n]), oacc[n], 0, 0, 0);
;               SB0; }
.LBB0_1149:
	s_waitcnt vmcnt(12)
	ds_read_b128 v[64:67], v203
	s_waitcnt vmcnt(9)
	ds_read_b128 v[68:71], v203 offset:8448
	ds_read2_b64 v[72:75], v201 offset1:4
	ds_read2_b64 v[76:79], v201 offset0:8 offset1:12
	ds_read_b128 v[80:83], v167 offset:64
	s_waitcnt vmcnt(7)
	ds_read_b128 v[84:87], v168 offset:64
	ds_read2_b64 v[88:91], v201 offset0:16 offset1:20
	s_waitcnt vmcnt(6)
	ds_read_b128 v[92:95], v203 offset:128
	s_waitcnt vmcnt(5)
	ds_read_b128 v[96:99], v203 offset:8576
	s_waitcnt lgkmcnt(6)
	v_mfma_f32_16x16x32_bf16 v[64:67], v[72:75], v[64:67], 0
	v_mfma_f32_16x16x32_bf16 v[68:71], v[72:75], v[68:71], 0
	ds_read2_b64 v[72:75], v201 offset0:24 offset1:28
	s_waitcnt vmcnt(4)
	ds_read_b128 v[100:103], v203 offset:192
	ds_read_b128 v[104:107], v203 offset:8640
	s_waitcnt lgkmcnt(7)
	v_mfma_f32_16x16x32_bf16 v[64:67], v[76:79], v[80:83], v[64:67]
	s_waitcnt lgkmcnt(6)
	v_mfma_f32_16x16x32_bf16 v[68:71], v[76:79], v[84:87], v[68:71]
	ds_read2_b64 v[76:79], v201 offset0:32 offset1:36
	ds_read_b128 v[80:83], v203 offset:256
	ds_read_b128 v[84:87], v203 offset:8704
	s_waitcnt lgkmcnt(7)
	v_mfma_f32_16x16x32_bf16 v[64:67], v[88:91], v[92:95], v[64:67]
	s_waitcnt lgkmcnt(6)
	v_mfma_f32_16x16x32_bf16 v[68:71], v[88:91], v[96:99], v[68:71]
	ds_read2_b64 v[88:91], v201 offset0:40 offset1:44
	ds_read_b128 v[92:95], v203 offset:320
	ds_read_b128 v[96:99], v203 offset:8768
	s_waitcnt lgkmcnt(7)
	v_mfma_f32_16x16x32_bf16 v[64:67], v[72:75], v[100:103], v[64:67]
	s_waitcnt lgkmcnt(6)
	v_mfma_f32_16x16x32_bf16 v[68:71], v[72:75], v[104:107], v[68:71]
	ds_read2_b64 v[72:75], v201 offset0:48 offset1:52
	ds_read_b128 v[100:103], v203 offset:384
	ds_read_b128 v[104:107], v203 offset:8832
	s_waitcnt lgkmcnt(7)
	v_mfma_f32_16x16x32_bf16 v[64:67], v[76:79], v[80:83], v[64:67]
	s_waitcnt lgkmcnt(6)
	v_mfma_f32_16x16x32_bf16 v[68:71], v[76:79], v[84:87], v[68:71]
	ds_read2_b64 v[76:79], v201 offset0:56 offset1:60
	ds_read_b128 v[80:83], v203 offset:448
	ds_read_b128 v[84:87], v203 offset:8896
	s_waitcnt lgkmcnt(7)
	v_mfma_f32_16x16x32_bf16 v[64:67], v[88:91], v[92:95], v[64:67]
	s_waitcnt lgkmcnt(6)
	v_mfma_f32_16x16x32_bf16 v[68:71], v[88:91], v[96:99], v[68:71]
	s_waitcnt lgkmcnt(4)
	v_mfma_f32_16x16x32_bf16 v[64:67], v[72:75], v[100:103], v[64:67]
	s_waitcnt lgkmcnt(3)
	v_mfma_f32_16x16x32_bf16 v[68:71], v[72:75], v[104:107], v[68:71]
	s_waitcnt lgkmcnt(1)
	v_mfma_f32_16x16x32_bf16 v[64:67], v[76:79], v[80:83], v[64:67]
	s_waitcnt lgkmcnt(0)
	v_mfma_f32_16x16x32_bf16 v[68:71], v[76:79], v[84:87], v[68:71]
	s_nop 5
	v_cndmask_b32_e64 v64, v64, 0, s[8:9]
	v_cndmask_b32_e64 v65, 0, v65, s[10:11]
	v_cndmask_b32_e64 v66, v66, 0, s[12:13]
	v_cndmask_b32_e64 v67, v67, 0, s[14:15]
	v_cvt_pk_bf16_f32 v64, v64, v65
	v_cvt_pk_bf16_f32 v65, v66, v67
	ds_write_b64 v204, v[64:65]
	v_cndmask_b32_e64 v64, v68, 0, s[16:17]
	v_cndmask_b32_e64 v65, 0, v69, s[18:19]
	v_cndmask_b32_e64 v66, v70, 0, s[20:21]
	v_cndmask_b32_e64 v67, v71, 0, s[22:23]
	v_cvt_pk_bf16_f32 v64, v64, v65
	v_cvt_pk_bf16_f32 v65, v66, v67
	ds_write_b64 v204, v[64:65] offset:2304
	ds_read_b128 v[64:67], v170
	ds_read_b128 v[68:71], v170 offset:8448
	ds_read_b128 v[72:75], v170 offset:16896
	ds_read_b128 v[76:79], v170 offset:25344
	ds_read_b128 v[80:83], v170 offset:64
	ds_read_b128 v[84:87], v170 offset:8512
	ds_read_b128 v[88:91], v170 offset:16960
	ds_read_b128 v[92:95], v170 offset:25408
	ds_read_b128 v[96:99], v170 offset:128
	ds_read_b128 v[100:103], v170 offset:8576
	ds_read_b128 v[104:107], v170 offset:17024
	ds_read_b128 v[108:111], v170 offset:25472
	v_cvt_pk_bf16_f32 v60, v60, v61
	v_cvt_pk_bf16_f32 v61, v62, v63
	v_cvt_pk_bf16_f32 v62, v56, v57
	v_cvt_pk_bf16_f32 v63, v58, v59
	s_waitcnt lgkmcnt(11)
	v_mfma_f32_16x16x32_bf16 v[56:59], v[60:63], v[64:67], 0
	s_waitcnt lgkmcnt(10)
	v_mfma_f32_16x16x32_bf16 v[64:67], v[60:63], v[68:71], 0
	s_waitcnt lgkmcnt(9)
	v_mfma_f32_16x16x32_bf16 v[68:71], v[60:63], v[72:75], 0
	s_waitcnt lgkmcnt(8)
	v_mfma_f32_16x16x32_bf16 v[60:63], v[60:63], v[76:79], 0
	ds_read_b128 v[72:75], v170 offset:192
	ds_read_b128 v[76:79], v170 offset:8640
	ds_read_b128 v[112:115], v170 offset:17088
	ds_read_b128 v[120:123], v170 offset:25536
	v_cvt_pk_bf16_f32 v52, v52, v53
	v_cvt_pk_bf16_f32 v53, v54, v55
	v_cvt_pk_bf16_f32 v54, v48, v49
	v_cvt_pk_bf16_f32 v55, v50, v51
	s_waitcnt lgkmcnt(11)
	v_mfma_f32_16x16x32_bf16 v[48:51], v[52:55], v[80:83], v[56:59]
	s_waitcnt lgkmcnt(10)
	v_mfma_f32_16x16x32_bf16 v[56:59], v[52:55], v[84:87], v[64:67]
	s_waitcnt lgkmcnt(9)
	v_mfma_f32_16x16x32_bf16 v[64:67], v[52:55], v[88:91], v[68:71]
	s_waitcnt lgkmcnt(8)
	v_mfma_f32_16x16x32_bf16 v[52:55], v[52:55], v[92:95], v[60:63]
	s_nop 2
	ds_read_b128 v[60:63], v170 offset:256
	ds_read_b128 v[68:71], v170 offset:8704
	ds_read_b128 v[80:83], v170 offset:17152
	ds_read_b128 v[84:87], v170 offset:25600
	v_cvt_pk_bf16_f32 v44, v44, v45
	v_cvt_pk_bf16_f32 v45, v46, v47
	v_cvt_pk_bf16_f32 v46, v40, v41
	v_cvt_pk_bf16_f32 v47, v42, v43
	s_waitcnt lgkmcnt(11)
	v_mfma_f32_16x16x32_bf16 v[40:43], v[44:47], v[96:99], v[48:51]
	s_waitcnt lgkmcnt(10)
	v_mfma_f32_16x16x32_bf16 v[48:51], v[44:47], v[100:103], v[56:59]
	s_waitcnt lgkmcnt(9)
	v_mfma_f32_16x16x32_bf16 v[56:59], v[44:47], v[104:107], v[64:67]
	s_waitcnt lgkmcnt(8)
; __device__ __forceinline__ void ret_unit(LAS unsigned char* lds, bf16_t* QKV, float* gn, int b, int h, int vs, bool commit, const float* s00p, const float* ss3, bool skel = false) {
;     ...
;           RC_LOAD(0); RC_LOAD(1); SB0;
; #pragma unroll
;           for (int kk = 0; kk < 8; ++kk) { if (kk + 2 < 8) RC_LOAD(kk + 2);
;               const u32x2 s0 = pack4(state[2 * kk]), s1 = pack4(state[2 * kk + 1]);
;               const u32x4 aw = (u32x4){s0.x, s0.y, s1.x, s1.y}; const bf16x8 afrag = __builtin_bit_cast(bf16x8, aw);
;               SB0;
; #pragma unroll
;               for (int n = 0; n < 4; ++n) oacc[n] = __builtin_amdgcn_mfma_f32_16x16x32_bf16(afrag, __builtin_bit_cast(bf16x8, qf[kk % 3][n]), oacc[n], 0, 0, 0);
;               SB0; }
;     ...
;         }
; #pragma unroll
;         for (int n = 0; n < 4; ++n) oacc[n] = oacc[n] * cd;
;         }
;         LDS_BAR();
;         if (c + 1 < 32) { RET_STAGE(Kn, Vn); if (c + 2 < 32) RET_LOAD(c + 2); }
;         if (!skel) {
;         bf16x8 vfrag[2];
;         { bf16x8 pf[2][4];
; #pragma unroll
;           for (int ks = 0; ks < 2; ++ks) { TR_FRAG(vfrag[ks], Vl, 136, 16 * w, ks);
; #pragma unroll
;               for (int n = 0; n < 4; ++n) pf[ks][n] = *(const LAS bf16x8*)(Pl + (16 * n + fr) * 72 + 32 * ks + 8 * fq); }
;           bf16x8 kf[3][2];
;     ...
;           RD_LOAD(0); RD_LOAD(1); SB0;
; #pragma unroll
;           for (int ks = 0; ks < 2; ++ks)
; #pragma unroll
;               for (int n = 0; n < 4; ++n) oacc[n] = __builtin_amdgcn_mfma_f32_16x16x32_bf16(vfrag[ks], pf[ks][n], oacc[n], 0, 0, 0);
;           SB0;
; #pragma unroll
;           for (int m = 0; m < 16; ++m) { if (m + 2 < 16) RD_LOAD(m + 2);
;               state[m] = state[m] * cd; SB0;
; #pragma unroll
;               for (int ks = 0; ks < 2; ++ks) state[m] = __builtin_amdgcn_mfma_f32_16x16x32_bf16(kf[m % 3][ks], vfrag[ks], state[m], 0, 0, 0);
;               SB0; }
;     ...
;         }
;         }
;     ...
; #pragma unroll
;         for (int n = 0; n < 4; ++n) { const f32x4 o = oacc[n];
;             float s1 = (o[0] + o[1]) + (o[2] + o[3]), s2 = (o[0] * o[0] + o[1] * o[1]) + (o[2] * o[2] + o[3] * o[3]);
;             s1 += __shfl_xor(s1, 16); s1 += __shfl_xor(s1, 32); s2 += __shfl_xor(s2, 16); s2 += __shfl_xor(s2, 32);
;             if (fq == 0) { atomicAdd((float*)(st + (16 * n + fr) * 2), s1); atomicAdd((float*)(st + (16 * n + fr) * 2 + 1), s2); }
	v_mfma_f32_16x16x32_bf16 v[44:47], v[44:47], v[108:111], v[52:55]
	s_nop 2
	ds_read_b128 v[52:55], v170 offset:320
	ds_read_b128 v[64:67], v170 offset:8768
	ds_read_b128 v[88:91], v170 offset:17216
	ds_read_b128 v[92:95], v170 offset:25664
	v_cvt_pk_bf16_f32 v36, v36, v37
	v_cvt_pk_bf16_f32 v37, v38, v39
	v_cvt_pk_bf16_f32 v38, v32, v33
	v_cvt_pk_bf16_f32 v39, v34, v35
	s_waitcnt lgkmcnt(11)
	v_mfma_f32_16x16x32_bf16 v[32:35], v[36:39], v[72:75], v[40:43]
	s_waitcnt lgkmcnt(10)
	v_mfma_f32_16x16x32_bf16 v[40:43], v[36:39], v[76:79], v[48:51]
	s_waitcnt lgkmcnt(9)
	v_mfma_f32_16x16x32_bf16 v[48:51], v[36:39], v[112:115], v[56:59]
	s_waitcnt lgkmcnt(8)
	v_mfma_f32_16x16x32_bf16 v[36:39], v[36:39], v[120:123], v[44:47]
	s_nop 2
	ds_read_b128 v[44:47], v170 offset:384
	ds_read_b128 v[56:59], v170 offset:8832
	ds_read_b128 v[72:75], v170 offset:17280
	ds_read_b128 v[76:79], v170 offset:25728
	v_cvt_pk_bf16_f32 v28, v28, v29
	v_cvt_pk_bf16_f32 v29, v30, v31
	v_cvt_pk_bf16_f32 v30, v24, v25
	v_cvt_pk_bf16_f32 v31, v26, v27
	s_waitcnt lgkmcnt(11)
	v_mfma_f32_16x16x32_bf16 v[24:27], v[28:31], v[60:63], v[32:35]
	s_waitcnt lgkmcnt(10)
	v_mfma_f32_16x16x32_bf16 v[32:35], v[28:31], v[68:71], v[40:43]
	s_waitcnt lgkmcnt(9)
	v_mfma_f32_16x16x32_bf16 v[40:43], v[28:31], v[80:83], v[48:51]
	s_waitcnt lgkmcnt(8)
	v_mfma_f32_16x16x32_bf16 v[28:31], v[28:31], v[84:87], v[36:39]
	s_nop 2
	ds_read_b128 v[36:39], v170 offset:448
	ds_read_b128 v[48:51], v170 offset:8896
	ds_read_b128 v[60:63], v170 offset:17344
	ds_read_b128 v[68:71], v170 offset:25792
	v_cvt_pk_bf16_f32 v20, v20, v21
	v_cvt_pk_bf16_f32 v21, v22, v23
	v_cvt_pk_bf16_f32 v22, v16, v17
	v_cvt_pk_bf16_f32 v23, v18, v19
	s_waitcnt lgkmcnt(11)
	v_mfma_f32_16x16x32_bf16 v[16:19], v[20:23], v[52:55], v[24:27]
	s_waitcnt lgkmcnt(10)
	v_mfma_f32_16x16x32_bf16 v[24:27], v[20:23], v[64:67], v[32:35]
	s_waitcnt lgkmcnt(9)
	v_mfma_f32_16x16x32_bf16 v[32:35], v[20:23], v[88:91], v[40:43]
	s_waitcnt lgkmcnt(8)
	v_mfma_f32_16x16x32_bf16 v[20:23], v[20:23], v[92:95], v[28:31]
	v_cvt_pk_bf16_f32 v12, v12, v13
	v_cvt_pk_bf16_f32 v13, v14, v15
	v_cvt_pk_bf16_f32 v14, v8, v9
	v_cvt_pk_bf16_f32 v15, v10, v11
	s_waitcnt lgkmcnt(7)
	v_mfma_f32_16x16x32_bf16 v[8:11], v[12:15], v[44:47], v[16:19]
	s_waitcnt lgkmcnt(6)
	v_mfma_f32_16x16x32_bf16 v[16:19], v[12:15], v[56:59], v[24:27]
	s_waitcnt lgkmcnt(5)
	v_mfma_f32_16x16x32_bf16 v[24:27], v[12:15], v[72:75], v[32:35]
	s_waitcnt lgkmcnt(4)
	v_mfma_f32_16x16x32_bf16 v[12:15], v[12:15], v[76:79], v[20:23]
	v_cvt_pk_bf16_f32 v4, v4, v5
	v_cvt_pk_bf16_f32 v5, v6, v7
	v_cvt_pk_bf16_f32 v6, v0, v1
	v_cvt_pk_bf16_f32 v7, v2, v3
	s_waitcnt lgkmcnt(3)
	v_mfma_f32_16x16x32_bf16 v[0:3], v[4:7], v[36:39], v[8:11]
	s_waitcnt lgkmcnt(2)
	v_mfma_f32_16x16x32_bf16 v[8:11], v[4:7], v[48:51], v[16:19]
	s_waitcnt lgkmcnt(1)
	v_mfma_f32_16x16x32_bf16 v[16:19], v[4:7], v[60:63], v[24:27]
	s_waitcnt lgkmcnt(0)
	v_mfma_f32_16x16x32_bf16 v[4:7], v[4:7], v[68:71], v[12:15]
	s_waitcnt lgkmcnt(0)
	s_barrier
	v_mov_b32_e32 v151, v150
	s_nop 3
	v_pk_mul_f32 v[14:15], v[150:151], v[18:19]
	v_pk_mul_f32 v[12:13], v[152:153], v[16:17]
	ds_read_b64_tr_b16 v[16:17], v200 offset:17408
	ds_read_b64_tr_b16 v[18:19], v200 offset:18496
	ds_read_b64_tr_b16 v[20:21], v200 offset:26112
	ds_read_b64_tr_b16 v[22:23], v200 offset:27200
	ds_read_b128 v[24:27], v205
	ds_read_b128 v[28:31], v205 offset:64
	ds_read_b128 v[32:35], v205 offset:2304
	ds_read_b128 v[36:39], v205 offset:2368
	ds_read_b128 v[40:43], v205 offset:4608
	ds_read_b128 v[44:47], v205 offset:4672
	ds_read_b128 v[48:51], v205 offset:6912
	ds_read_b128 v[52:55], v205 offset:6976
	v_pk_mul_f32 v[6:7], v[150:151], v[6:7]
	v_pk_mul_f32 v[4:5], v[152:153], v[4:5]
	v_pk_mul_f32 v[10:11], v[150:151], v[10:11]
	v_pk_mul_f32 v[8:9], v[152:153], v[8:9]
	v_pk_mul_f32 v[2:3], v[150:151], v[2:3]
	v_pk_mul_f32 v[0:1], v[152:153], v[0:1]
	s_waitcnt lgkmcnt(7)
	s_nop 0
	v_mfma_f32_16x16x32_bf16 v[0:3], v[16:19], v[24:27], v[0:3]
	s_waitcnt lgkmcnt(5)
	v_mfma_f32_16x16x32_bf16 v[8:11], v[16:19], v[32:35], v[8:11]
	s_waitcnt lgkmcnt(3)
	v_mfma_f32_16x16x32_bf16 v[24:27], v[16:19], v[40:43], v[12:15]
	s_waitcnt lgkmcnt(1)
	v_mfma_f32_16x16x32_bf16 v[16:19], v[16:19], v[48:51], v[4:7]
	v_mfma_f32_16x16x32_bf16 v[12:15], v[20:23], v[28:31], v[0:3]
	v_mfma_f32_16x16x32_bf16 v[8:11], v[20:23], v[36:39], v[8:11]
	v_mfma_f32_16x16x32_bf16 v[4:7], v[20:23], v[44:47], v[24:27]
	s_waitcnt lgkmcnt(0)
	v_mfma_f32_16x16x32_bf16 v[0:3], v[20:23], v[52:55], v[16:19]
	s_nop 3
	v_add_f32_e32 v16, v12, v13
	v_add_f32_e32 v17, v14, v15
	v_add_f32_e32 v16, v16, v17
	v_mul_f32_e32 v17, v13, v13
	v_mul_f32_e32 v18, v15, v15
	v_fmac_f32_e32 v17, v12, v12
	v_fmac_f32_e32 v18, v14, v14
	v_add_f32_e32 v18, v17, v18
	ds_bpermute_b32 v19, v118, v16
	ds_bpermute_b32 v20, v118, v18
	s_waitcnt lgkmcnt(1)
	v_add_f32_e32 v16, v16, v19
	s_waitcnt lgkmcnt(0)
	v_add_f32_e32 v18, v18, v20
	ds_bpermute_b32 v17, v119, v16
	ds_bpermute_b32 v19, v119, v18
	s_and_saveexec_b64 s[64:65], s[6:7]
	s_cbranch_execz .LBB0_1151
	s_waitcnt lgkmcnt(1)
	v_add_f32_e32 v16, v16, v17
	v_add_u32_e32 v17, 0, v166
	v_add_u32_e32 v17, 0x23800, v17
	s_waitcnt lgkmcnt(0)
	v_add_f32_e32 v18, v18, v19
	ds_add_f32 v17, v16
	ds_add_f32 v17, v18 offset:4
